# v76 + final rmsnorm (phase 16) processes 4 rows per wave iteration with 16 loads in flight and counted vmcnt
# speedup vs baseline: 1.0188x; 1.0008x over previous
.LBB0_1459:
	s_cmp_lt_i32 s38, 17
	s_cselect_b64 s[4:5], -1, 0
	s_and_b64 s[0:1], s[4:5], s[0:1]
	s_andn2_b64 vcc, exec, s[0:1]
	s_cbranch_vccnz .LBB0_1480
	s_mov_b32 s0, 0x10000
	v_mov_b32_e32 v1, s84
	v_add_co_u32_e32 v4, vcc, 0x2d500000, v1
	v_mov_b32_e32 v1, s85
	s_nop 0
	v_addc_co_u32_e32 v5, vcc, 0, v1, vcc
	flat_load_dwordx2 v[18:19], v[4:5] offset:280
	s_waitcnt lgkmcnt(0)
	flat_load_dwordx2 v[2:3], v[4:5] offset:264
	v_and_b32_e32 v4, 0x3ff, v0
	v_mov_b32_e32 v1, v4
	s_nop 0
	v_ashrrev_i32_e32 v4, 6, v4
	v_lshl_add_u32 v34, s82, 2, v4
	v_cmp_gt_i32_e32 vcc, s0, v34
	s_and_saveexec_b64 s[2:3], vcc
	s_cbranch_execz .LBB0_1479
	v_and_b32_e32 v24, 63, v1
	v_lshlrev_b32_e32 v20, 4, v24
	v_mov_b32_e32 v21, 0
	s_waitcnt vmcnt(0) lgkmcnt(0)
	v_lshl_add_u64 v[22:23], v[2:3], 0, v[20:21]
	flat_load_dwordx4 v[2:5], v[22:23]
	flat_load_dwordx4 v[6:9], v[22:23] offset:1024
	flat_load_dwordx4 v[10:13], v[22:23] offset:2048
	flat_load_dwordx4 v[14:17], v[22:23] offset:3072
	v_mbcnt_lo_u32_b32 v1, -1, 0
	v_mbcnt_hi_u32_b32 v21, -1, v1
	v_and_b32_e32 v1, 64, v21
	v_add_u32_e32 v22, 64, v1
	v_xor_b32_e32 v1, 32, v21
	v_cmp_lt_i32_e64 s[0:1], v1, v22
	v_xor_b32_e32 v23, 16, v21
	v_ashrrev_i32_e32 v35, 31, v34
	v_cndmask_b32_e64 v1, v21, v1, s[0:1]
	v_cmp_lt_i32_e64 s[0:1], v23, v22
	s_lshl_b32 s6, s40, 2
	v_lshlrev_b64 v[36:37], 11, v[34:35]
	v_cndmask_b32_e64 v23, v21, v23, s[0:1]
	v_lshlrev_b32_e32 v42, 2, v23
	v_xor_b32_e32 v23, 8, v21
	v_cmp_lt_i32_e64 s[0:1], v23, v22
	s_ashr_i32 s7, s6, 31
	s_mov_b64 s[8:9], 0
	v_cndmask_b32_e64 v23, v21, v23, s[0:1]
	v_lshlrev_b32_e32 v43, 2, v23
	v_xor_b32_e32 v23, 4, v21
	v_cmp_lt_i32_e64 s[0:1], v23, v22
	v_cmp_ne_u64_e32 vcc, 0, v[18:19]
	v_lshlrev_b32_e32 v1, 2, v1
	v_cndmask_b32_e64 v23, v21, v23, s[0:1]
	v_lshlrev_b32_e32 v44, 2, v23
	v_xor_b32_e32 v23, 2, v21
	v_cmp_lt_i32_e64 s[0:1], v23, v22
	v_lshl_or_b32 v36, v24, 3, v36
	s_lshl_b64 s[10:11], s[6:7], 11
	v_cndmask_b32_e64 v23, v21, v23, s[0:1]
	v_lshlrev_b32_e32 v45, 2, v23
	v_xor_b32_e32 v23, 1, v21
	v_cmp_lt_i32_e64 s[0:1], v23, v22
	s_lshl_b64 s[12:13], s[6:7], 12
	s_mov_b32 s7, 0x800000
	v_cndmask_b32_e64 v21, v21, v23, s[0:1]
	v_lshlrev_b64 v[22:23], 12, v[34:35]
	v_or_b32_e32 v22, v22, v20
	v_lshlrev_b32_e32 v46, 2, v21
	v_lshl_add_u64 v[38:39], v[18:19], 0, v[22:23]
	v_mov_b32_e32 v35, 0x358637bd
	s_mov_b32 s14, 0xffff
	s_waitcnt vmcnt(0) lgkmcnt(0)
	s_mul_i32 s87, s6, 3
	s_lshl_b32 s88, s6, 2
	s_lshl_b64 s[90:91], s[12:13], 2
	s_lshl_b64 s[92:93], s[10:11], 2
	s_lshl_b64 s[94:95], s[12:13], 1
	s_add_u32 s96, s94, s12
	s_addc_u32 s97, s95, s13
.Lnorm4_top:
	v_readfirstlane_b32 s86, v34
	s_cmp_gt_i32 s86, s14
	s_cbranch_scc1 .LBB0_1479
	s_add_i32 s86, s86, s87
	s_cmp_gt_i32 s86, s14
	s_cbranch_scc1 .LBB0_1463
	v_lshl_add_u64 v[52:53], v[38:39], 0, s[12:13]
	v_lshl_add_u64 v[54:55], v[38:39], 0, s[94:95]
	v_lshl_add_u64 v[56:57], v[38:39], 0, s[96:97]
	global_load_dwordx4 v[100:103], v[38:39], off
	global_load_dwordx4 v[104:107], v[38:39], off offset:1024
	global_load_dwordx4 v[108:111], v[38:39], off offset:2048
	global_load_dwordx4 v[112:115], v[38:39], off offset:3072
	global_load_dwordx4 v[116:119], v[52:53], off
	global_load_dwordx4 v[120:123], v[52:53], off offset:1024
	global_load_dwordx4 v[124:127], v[52:53], off offset:2048
	global_load_dwordx4 v[128:131], v[52:53], off offset:3072
	global_load_dwordx4 v[132:135], v[54:55], off
	global_load_dwordx4 v[136:139], v[54:55], off offset:1024
	global_load_dwordx4 v[140:143], v[54:55], off offset:2048
	global_load_dwordx4 v[144:147], v[54:55], off offset:3072
	global_load_dwordx4 v[148:151], v[56:57], off
	global_load_dwordx4 v[152:155], v[56:57], off offset:1024
	global_load_dwordx4 v[156:159], v[56:57], off offset:2048
	global_load_dwordx4 v[160:163], v[56:57], off offset:3072
	s_waitcnt vmcnt(12)
	v_mul_f32_e32 v48, v101, v101
	v_fmac_f32_e32 v48, v100, v100
	v_fmac_f32_e32 v48, v102, v102
	v_fmac_f32_e32 v48, v103, v103
	v_mul_f32_e32 v49, v105, v105
	v_fmac_f32_e32 v49, v104, v104
	v_fmac_f32_e32 v49, v106, v106
	v_fmac_f32_e32 v49, v107, v107
	v_mul_f32_e32 v50, v109, v109
	v_fmac_f32_e32 v50, v108, v108
	v_fmac_f32_e32 v50, v110, v110
	v_fmac_f32_e32 v50, v111, v111
	v_mul_f32_e32 v51, v113, v113
	v_fmac_f32_e32 v51, v112, v112
	v_fmac_f32_e32 v51, v114, v114
	v_fmac_f32_e32 v51, v115, v115
	v_add_f32_e32 v47, v48, v49
	v_add_f32_e32 v40, v47, v50
	v_add_f32_e32 v40, v40, v51
	ds_bpermute_b32 v41, v1, v40
	s_waitcnt lgkmcnt(0)
	v_add_f32_e32 v40, v40, v41
	ds_bpermute_b32 v41, v42, v40
	s_waitcnt lgkmcnt(0)
	v_add_f32_e32 v40, v40, v41
	ds_bpermute_b32 v41, v43, v40
	s_waitcnt lgkmcnt(0)
	v_add_f32_e32 v40, v40, v41
	ds_bpermute_b32 v41, v44, v40
	s_waitcnt lgkmcnt(0)
	v_add_f32_e32 v40, v40, v41
	ds_bpermute_b32 v41, v45, v40
	s_waitcnt lgkmcnt(0)
	v_add_f32_e32 v40, v40, v41
	ds_bpermute_b32 v41, v46, v40
	s_waitcnt lgkmcnt(0)
	v_add_f32_e32 v40, v40, v41
	v_fmamk_f32 v40, v40, 0x3a800000, v35
	v_mul_f32_e32 v41, 0x4b800000, v40
	v_cmp_gt_f32_e64 s[0:1], s7, v40
	s_nop 1
	v_cndmask_b32_e64 v40, v40, v41, s[0:1]
	v_rsq_f32_e32 v40, v40
	s_nop 0
	v_mul_f32_e32 v41, 0x45800000, v40
	v_cndmask_b32_e64 v40, v40, v41, s[0:1]
	v_pk_mul_f32 v[100:101], v[100:101], v[40:41] op_sel_hi:[1,0]
	v_pk_mul_f32 v[102:103], v[102:103], v[40:41] op_sel_hi:[1,0]
	v_pk_mul_f32 v[100:101], v[2:3], v[100:101]
	v_pk_mul_f32 v[102:103], v[4:5], v[102:103]
	global_store_dwordx4 v[38:39], v[100:103], off
	v_pk_mul_f32 v[104:105], v[104:105], v[40:41] op_sel_hi:[1,0]
	v_pk_mul_f32 v[106:107], v[106:107], v[40:41] op_sel_hi:[1,0]
	v_pk_mul_f32 v[104:105], v[6:7], v[104:105]
	v_pk_mul_f32 v[106:107], v[8:9], v[106:107]
	global_store_dwordx4 v[38:39], v[104:107], off offset:1024
	v_pk_mul_f32 v[108:109], v[108:109], v[40:41] op_sel_hi:[1,0]
	v_pk_mul_f32 v[110:111], v[110:111], v[40:41] op_sel_hi:[1,0]
	v_pk_mul_f32 v[108:109], v[10:11], v[108:109]
	v_pk_mul_f32 v[110:111], v[12:13], v[110:111]
	global_store_dwordx4 v[38:39], v[108:111], off offset:2048
	v_pk_mul_f32 v[112:113], v[112:113], v[40:41] op_sel_hi:[1,0]
	v_pk_mul_f32 v[114:115], v[114:115], v[40:41] op_sel_hi:[1,0]
	v_pk_mul_f32 v[112:113], v[14:15], v[112:113]
	v_pk_mul_f32 v[114:115], v[16:17], v[114:115]
	global_store_dwordx4 v[38:39], v[112:115], off offset:3072
	s_waitcnt vmcnt(12)
	v_mul_f32_e32 v48, v117, v117
	v_fmac_f32_e32 v48, v116, v116
	v_fmac_f32_e32 v48, v118, v118
	v_fmac_f32_e32 v48, v119, v119
	v_mul_f32_e32 v49, v121, v121
	v_fmac_f32_e32 v49, v120, v120
	v_fmac_f32_e32 v49, v122, v122
	v_fmac_f32_e32 v49, v123, v123
	v_mul_f32_e32 v50, v125, v125
	v_fmac_f32_e32 v50, v124, v124
	v_fmac_f32_e32 v50, v126, v126
	v_fmac_f32_e32 v50, v127, v127
	v_mul_f32_e32 v51, v129, v129
	v_fmac_f32_e32 v51, v128, v128
	v_fmac_f32_e32 v51, v130, v130
	v_fmac_f32_e32 v51, v131, v131
	v_add_f32_e32 v47, v48, v49
	v_add_f32_e32 v40, v47, v50
	v_add_f32_e32 v40, v40, v51
	ds_bpermute_b32 v41, v1, v40
	s_waitcnt lgkmcnt(0)
	v_add_f32_e32 v40, v40, v41
	ds_bpermute_b32 v41, v42, v40
	s_waitcnt lgkmcnt(0)
	v_add_f32_e32 v40, v40, v41
	ds_bpermute_b32 v41, v43, v40
	s_waitcnt lgkmcnt(0)
	v_add_f32_e32 v40, v40, v41
	ds_bpermute_b32 v41, v44, v40
	s_waitcnt lgkmcnt(0)
	v_add_f32_e32 v40, v40, v41
	ds_bpermute_b32 v41, v45, v40
	s_waitcnt lgkmcnt(0)
	v_add_f32_e32 v40, v40, v41
	ds_bpermute_b32 v41, v46, v40
	s_waitcnt lgkmcnt(0)
	v_add_f32_e32 v40, v40, v41
	v_fmamk_f32 v40, v40, 0x3a800000, v35
	v_mul_f32_e32 v41, 0x4b800000, v40
	v_cmp_gt_f32_e64 s[0:1], s7, v40
	s_nop 1
	v_cndmask_b32_e64 v40, v40, v41, s[0:1]
	v_rsq_f32_e32 v40, v40
	s_nop 0
	v_mul_f32_e32 v41, 0x45800000, v40
	v_cndmask_b32_e64 v40, v40, v41, s[0:1]
	v_pk_mul_f32 v[116:117], v[116:117], v[40:41] op_sel_hi:[1,0]
	v_pk_mul_f32 v[118:119], v[118:119], v[40:41] op_sel_hi:[1,0]
	v_pk_mul_f32 v[116:117], v[2:3], v[116:117]
	v_pk_mul_f32 v[118:119], v[4:5], v[118:119]
	global_store_dwordx4 v[52:53], v[116:119], off
	v_pk_mul_f32 v[120:121], v[120:121], v[40:41] op_sel_hi:[1,0]
	v_pk_mul_f32 v[122:123], v[122:123], v[40:41] op_sel_hi:[1,0]
	v_pk_mul_f32 v[120:121], v[6:7], v[120:121]
	v_pk_mul_f32 v[122:123], v[8:9], v[122:123]
	global_store_dwordx4 v[52:53], v[120:123], off offset:1024
	v_pk_mul_f32 v[124:125], v[124:125], v[40:41] op_sel_hi:[1,0]
	v_pk_mul_f32 v[126:127], v[126:127], v[40:41] op_sel_hi:[1,0]
	v_pk_mul_f32 v[124:125], v[10:11], v[124:125]
	v_pk_mul_f32 v[126:127], v[12:13], v[126:127]
	global_store_dwordx4 v[52:53], v[124:127], off offset:2048
	v_pk_mul_f32 v[128:129], v[128:129], v[40:41] op_sel_hi:[1,0]
	v_pk_mul_f32 v[130:131], v[130:131], v[40:41] op_sel_hi:[1,0]
	v_pk_mul_f32 v[128:129], v[14:15], v[128:129]
	v_pk_mul_f32 v[130:131], v[16:17], v[130:131]
	global_store_dwordx4 v[52:53], v[128:131], off offset:3072
	s_waitcnt vmcnt(12)
	v_mul_f32_e32 v48, v133, v133
	v_fmac_f32_e32 v48, v132, v132
	v_fmac_f32_e32 v48, v134, v134
	v_fmac_f32_e32 v48, v135, v135
	v_mul_f32_e32 v49, v137, v137
	v_fmac_f32_e32 v49, v136, v136
	v_fmac_f32_e32 v49, v138, v138
	v_fmac_f32_e32 v49, v139, v139
	v_mul_f32_e32 v50, v141, v141
	v_fmac_f32_e32 v50, v140, v140
	v_fmac_f32_e32 v50, v142, v142
	v_fmac_f32_e32 v50, v143, v143
	v_mul_f32_e32 v51, v145, v145
	v_fmac_f32_e32 v51, v144, v144
	v_fmac_f32_e32 v51, v146, v146
	v_fmac_f32_e32 v51, v147, v147
	v_add_f32_e32 v47, v48, v49
	v_add_f32_e32 v40, v47, v50
	v_add_f32_e32 v40, v40, v51
	ds_bpermute_b32 v41, v1, v40
	s_waitcnt lgkmcnt(0)
	v_add_f32_e32 v40, v40, v41
	ds_bpermute_b32 v41, v42, v40
	s_waitcnt lgkmcnt(0)
	v_add_f32_e32 v40, v40, v41
	ds_bpermute_b32 v41, v43, v40
	s_waitcnt lgkmcnt(0)
	v_add_f32_e32 v40, v40, v41
	ds_bpermute_b32 v41, v44, v40
	s_waitcnt lgkmcnt(0)
	v_add_f32_e32 v40, v40, v41
	ds_bpermute_b32 v41, v45, v40
	s_waitcnt lgkmcnt(0)
	v_add_f32_e32 v40, v40, v41
	ds_bpermute_b32 v41, v46, v40
	s_waitcnt lgkmcnt(0)
	v_add_f32_e32 v40, v40, v41
	v_fmamk_f32 v40, v40, 0x3a800000, v35
	v_mul_f32_e32 v41, 0x4b800000, v40
	v_cmp_gt_f32_e64 s[0:1], s7, v40
	s_nop 1
	v_cndmask_b32_e64 v40, v40, v41, s[0:1]
	v_rsq_f32_e32 v40, v40
	s_nop 0
	v_mul_f32_e32 v41, 0x45800000, v40
	v_cndmask_b32_e64 v40, v40, v41, s[0:1]
	v_pk_mul_f32 v[132:133], v[132:133], v[40:41] op_sel_hi:[1,0]
	v_pk_mul_f32 v[134:135], v[134:135], v[40:41] op_sel_hi:[1,0]
	v_pk_mul_f32 v[132:133], v[2:3], v[132:133]
	v_pk_mul_f32 v[134:135], v[4:5], v[134:135]
	global_store_dwordx4 v[54:55], v[132:135], off
	v_pk_mul_f32 v[136:137], v[136:137], v[40:41] op_sel_hi:[1,0]
	v_pk_mul_f32 v[138:139], v[138:139], v[40:41] op_sel_hi:[1,0]
	v_pk_mul_f32 v[136:137], v[6:7], v[136:137]
	v_pk_mul_f32 v[138:139], v[8:9], v[138:139]
	global_store_dwordx4 v[54:55], v[136:139], off offset:1024
	v_pk_mul_f32 v[140:141], v[140:141], v[40:41] op_sel_hi:[1,0]
	v_pk_mul_f32 v[142:143], v[142:143], v[40:41] op_sel_hi:[1,0]
	v_pk_mul_f32 v[140:141], v[10:11], v[140:141]
	v_pk_mul_f32 v[142:143], v[12:13], v[142:143]
	global_store_dwordx4 v[54:55], v[140:143], off offset:2048
	v_pk_mul_f32 v[144:145], v[144:145], v[40:41] op_sel_hi:[1,0]
	v_pk_mul_f32 v[146:147], v[146:147], v[40:41] op_sel_hi:[1,0]
	v_pk_mul_f32 v[144:145], v[14:15], v[144:145]
	v_pk_mul_f32 v[146:147], v[16:17], v[146:147]
	global_store_dwordx4 v[54:55], v[144:147], off offset:3072
	s_waitcnt vmcnt(12)
	v_mul_f32_e32 v48, v149, v149
	v_fmac_f32_e32 v48, v148, v148
	v_fmac_f32_e32 v48, v150, v150
	v_fmac_f32_e32 v48, v151, v151
	v_mul_f32_e32 v49, v153, v153
	v_fmac_f32_e32 v49, v152, v152
	v_fmac_f32_e32 v49, v154, v154
	v_fmac_f32_e32 v49, v155, v155
	v_mul_f32_e32 v50, v157, v157
	v_fmac_f32_e32 v50, v156, v156
	v_fmac_f32_e32 v50, v158, v158
	v_fmac_f32_e32 v50, v159, v159
	v_mul_f32_e32 v51, v161, v161
	v_fmac_f32_e32 v51, v160, v160
	v_fmac_f32_e32 v51, v162, v162
	v_fmac_f32_e32 v51, v163, v163
	v_add_f32_e32 v47, v48, v49
	v_add_f32_e32 v40, v47, v50
	v_add_f32_e32 v40, v40, v51
	ds_bpermute_b32 v41, v1, v40
	s_waitcnt lgkmcnt(0)
	v_add_f32_e32 v40, v40, v41
	ds_bpermute_b32 v41, v42, v40
	s_waitcnt lgkmcnt(0)
	v_add_f32_e32 v40, v40, v41
	ds_bpermute_b32 v41, v43, v40
	s_waitcnt lgkmcnt(0)
	v_add_f32_e32 v40, v40, v41
	ds_bpermute_b32 v41, v44, v40
	s_waitcnt lgkmcnt(0)
	v_add_f32_e32 v40, v40, v41
	ds_bpermute_b32 v41, v45, v40
	s_waitcnt lgkmcnt(0)
	v_add_f32_e32 v40, v40, v41
	ds_bpermute_b32 v41, v46, v40
	s_waitcnt lgkmcnt(0)
	v_add_f32_e32 v40, v40, v41
	v_fmamk_f32 v40, v40, 0x3a800000, v35
	v_mul_f32_e32 v41, 0x4b800000, v40
	v_cmp_gt_f32_e64 s[0:1], s7, v40
	s_nop 1
	v_cndmask_b32_e64 v40, v40, v41, s[0:1]
	v_rsq_f32_e32 v40, v40
	s_nop 0
	v_mul_f32_e32 v41, 0x45800000, v40
	v_cndmask_b32_e64 v40, v40, v41, s[0:1]
	v_pk_mul_f32 v[148:149], v[148:149], v[40:41] op_sel_hi:[1,0]
	v_pk_mul_f32 v[150:151], v[150:151], v[40:41] op_sel_hi:[1,0]
	v_pk_mul_f32 v[148:149], v[2:3], v[148:149]
	v_pk_mul_f32 v[150:151], v[4:5], v[150:151]
	global_store_dwordx4 v[56:57], v[148:151], off
	v_pk_mul_f32 v[152:153], v[152:153], v[40:41] op_sel_hi:[1,0]
	v_pk_mul_f32 v[154:155], v[154:155], v[40:41] op_sel_hi:[1,0]
	v_pk_mul_f32 v[152:153], v[6:7], v[152:153]
	v_pk_mul_f32 v[154:155], v[8:9], v[154:155]
	global_store_dwordx4 v[56:57], v[152:155], off offset:1024
	v_pk_mul_f32 v[156:157], v[156:157], v[40:41] op_sel_hi:[1,0]
	v_pk_mul_f32 v[158:159], v[158:159], v[40:41] op_sel_hi:[1,0]
	v_pk_mul_f32 v[156:157], v[10:11], v[156:157]
	v_pk_mul_f32 v[158:159], v[12:13], v[158:159]
	global_store_dwordx4 v[56:57], v[156:159], off offset:2048
	v_pk_mul_f32 v[160:161], v[160:161], v[40:41] op_sel_hi:[1,0]
	v_pk_mul_f32 v[162:163], v[162:163], v[40:41] op_sel_hi:[1,0]
	v_pk_mul_f32 v[160:161], v[14:15], v[160:161]
	v_pk_mul_f32 v[162:163], v[16:17], v[162:163]
	global_store_dwordx4 v[56:57], v[160:163], off offset:3072
	v_add_u32_e32 v34, s88, v34
	v_lshl_add_u64 v[38:39], v[38:39], 0, s[90:91]
	v_lshl_add_u64 v[36:37], v[36:37], 0, s[92:93]
	s_branch .Lnorm4_top
